# v30 + EpiUp silu mul/add packed into v_pk_mul_f32/v_pk_add_f32 (45 pairs, bit-identical math)
# speedup vs baseline: 1.0066x; 1.0066x over previous
; #define PG8_STAGE(bufoff, gbase, voff) do { _Pragma("unroll") for (int _i = 0; _i < 2; ++_i) glds16_s((gbase), (voff)[_i], ldsb + (unsigned)((bufoff) + _i * 8192)); } while (0)
; #define PG8_LDA(dst, b, h) do { _Pragma("unroll") for (int m = 0; m < 4; ++m) _Pragma("unroll") for (int k = 0; k < 2; ++k) dst[m][k] = *(const LAS h16x8*)(lds + PG8_SA(b, h) + aoff + m * 2048 + k * 1024); } while (0)
; #define PG8_LDB(dst, b, h) do { _Pragma("unroll") for (int n = 0; n < 2; ++n) _Pragma("unroll") for (int k = 0; k < 2; ++k) dst[n][k] = *(const LAS h16x8*)(lds + PG8_SB(b, h) + boff + n * 2048 + k * 1024); } while (0)
; #define PG8_MMA(ai, bj, At, Bt) do { __builtin_amdgcn_s_setprio(1); _Pragma("unroll") for (int m = 0; m < 4; ++m) _Pragma("unroll") for (int n = 0; n < 2; ++n) _Pragma("unroll") for (int k = 0; k < 2; ++k) \
;         acc[ai][bj][m][n] = mma_step<I8>(Bt[n][k], At[m][k], acc[ai][bj][m][n]); __builtin_amdgcn_s_setprio(0); } while (0)
; #define PG8_WAIT_V(n) asm volatile("s_waitcnt vmcnt(" #n ")" ::: "memory")
; #define PG8_WAIT_L(n) asm volatile("s_waitcnt lgkmcnt(" #n ")" ::: "memory")
; #define PG8_BAR __builtin_amdgcn_s_barrier()
; #define PG8_SCHED __builtin_amdgcn_sched_barrier(0)
; template <class Prob, class Epi, bool I8 = false, bool ALIGN_EPI = true, bool SP2 = true>
; __device__ __forceinline__ void gemm_phase(LAS unsigned char* lds, int wave, const Prob& P, const Epi& E) {
;     ...
;             if constexpr (SP2) {
;             PG8_LDB(B0, 0, 0); PG8_LDB(B1, 0, 1); PG8_SCHED; PG8_LDA(At, 0, 0); PG8_STAGE(PG8_SA(1, 1), a1 + hstepA, voffA);
;             PG8_WAIT_V(8); PG8_WAIT_L(0); PG8_BAR; PG8_MMA(0, 0, At, B0); PG8_MMA(0, 1, At, B1); PG8_BAR; PG8_SCHED;
;             PG8_LDA(At, 0, 1); PG8_STAGE(PG8_SB(0, 0), b2, voffB); PG8_STAGE(PG8_SB(0, 1), b2 + hstepB, voffB); PG8_STAGE(PG8_SA(0, 0), a2, voffA);
.LBB0_1065:
	v_add_u32_e32 v124, 0x10000, v210
	v_add_u32_e32 v140, 0x14000, v210
	ds_read_b128 v[104:107], v124
	ds_read_b128 v[112:115], v124 offset:1024
	ds_read_b128 v[120:123], v124 offset:2048
	ds_read_b128 v[124:127], v124 offset:3072
	ds_read_b128 v[128:131], v140
	ds_read_b128 v[132:135], v140 offset:1024
	ds_read_b128 v[136:139], v140 offset:2048
	ds_read_b128 v[140:143], v140 offset:3072
	s_cmp_eq_u32 s4, 12
	s_cselect_b32 s62, s96, vcc_lo
	s_cselect_b32 s63, s51, vcc_hi
	s_cselect_b32 s68, s97, s0
	s_cselect_b32 s69, s49, s1
	s_add_u32 s60, s62, 0x80
	s_addc_u32 s61, s63, 0
	ds_read_b128 v[144:147], v211
	ds_read_b128 v[164:167], v211 offset:1024
	ds_read_b128 v[168:171], v211 offset:2048
	ds_read_b128 v[172:175], v211 offset:3072
	ds_read_b128 v[176:179], v211 offset:4096
	ds_read_b128 v[180:183], v211 offset:5120
	ds_read_b128 v[184:187], v211 offset:6144
	ds_read_b128 v[188:191], v211 offset:7168
	s_mov_b32 s5, m0
	s_mov_b32 m0, s90
	s_nop 0
	global_load_lds_dwordx4 v250, s[44:45]
	s_mov_b32 m0, s5
	s_nop 0
	s_mov_b32 s5, m0
	s_mov_b32 m0, s92
	s_nop 0
	global_load_lds_dwordx4 v247, s[44:45]
	s_mov_b32 m0, s5
	s_waitcnt vmcnt(8)
	s_waitcnt lgkmcnt(0)
	s_barrier
	s_setprio 1
	s_waitcnt lgkmcnt(7)
	v_mfma_i32_16x16x64_i8 v[160:163], v[104:107], v[144:147], v[160:163]
	v_mfma_i32_16x16x64_i8 v[152:155], v[120:123], v[144:147], v[152:155]
	s_waitcnt lgkmcnt(5)
	v_mfma_i32_16x16x64_i8 v[52:55], v[104:107], v[168:171], v[52:55]
	v_mfma_i32_16x16x64_i8 v[80:83], v[120:123], v[168:171], v[80:83]
	s_waitcnt lgkmcnt(3)
	v_mfma_i32_16x16x64_i8 v[48:51], v[104:107], v[176:179], v[48:51]
	v_mfma_i32_16x16x64_i8 v[72:75], v[120:123], v[176:179], v[72:75]
	s_waitcnt lgkmcnt(1)
	v_mfma_i32_16x16x64_i8 v[44:47], v[104:107], v[184:187], v[44:47]
	v_mfma_i32_16x16x64_i8 v[68:71], v[120:123], v[184:187], v[68:71]
	v_mfma_i32_16x16x64_i8 v[160:163], v[112:115], v[164:167], v[160:163]
	v_mfma_i32_16x16x64_i8 v[152:155], v[124:127], v[164:167], v[152:155]
	v_mfma_i32_16x16x64_i8 v[52:55], v[112:115], v[172:175], v[52:55]
	v_mfma_i32_16x16x64_i8 v[80:83], v[124:127], v[172:175], v[80:83]
	v_mfma_i32_16x16x64_i8 v[48:51], v[112:115], v[180:183], v[48:51]
	v_mfma_i32_16x16x64_i8 v[72:75], v[124:127], v[180:183], v[72:75]
	s_waitcnt lgkmcnt(0)
	v_mfma_i32_16x16x64_i8 v[44:47], v[112:115], v[188:191], v[44:47]
	v_mfma_i32_16x16x64_i8 v[68:71], v[124:127], v[188:191], v[68:71]
	s_setprio 0
	s_setprio 1
	v_mfma_i32_16x16x64_i8 v[116:119], v[128:131], v[144:147], v[116:119]
	v_mfma_i32_16x16x64_i8 v[28:31], v[136:139], v[144:147], v[28:31]
	v_mfma_i32_16x16x64_i8 v[100:103], v[128:131], v[168:171], v[100:103]
	v_mfma_i32_16x16x64_i8 v[24:27], v[136:139], v[168:171], v[24:27]
	v_mfma_i32_16x16x64_i8 v[96:99], v[128:131], v[176:179], v[96:99]
	v_mfma_i32_16x16x64_i8 v[20:23], v[136:139], v[176:179], v[20:23]
	v_mfma_i32_16x16x64_i8 v[92:95], v[128:131], v[184:187], v[92:95]
	v_mfma_i32_16x16x64_i8 v[16:19], v[136:139], v[184:187], v[16:19]
	v_mfma_i32_16x16x64_i8 v[116:119], v[132:135], v[164:167], v[116:119]
	v_mfma_i32_16x16x64_i8 v[28:31], v[140:143], v[164:167], v[28:31]
	v_mfma_i32_16x16x64_i8 v[100:103], v[132:135], v[172:175], v[100:103]
	v_mfma_i32_16x16x64_i8 v[24:27], v[140:143], v[172:175], v[24:27]
	v_mfma_i32_16x16x64_i8 v[96:99], v[132:135], v[180:183], v[96:99]
	v_mfma_i32_16x16x64_i8 v[20:23], v[140:143], v[180:183], v[20:23]
	v_mfma_i32_16x16x64_i8 v[92:95], v[132:135], v[188:191], v[92:95]
	v_mfma_i32_16x16x64_i8 v[16:19], v[140:143], v[188:191], v[16:19]
	s_setprio 0
	s_barrier
	ds_read_b128 v[144:147], v211 offset:16384
	ds_read_b128 v[164:167], v211 offset:17408
	ds_read_b128 v[168:171], v211 offset:18432
	ds_read_b128 v[172:175], v211 offset:19456
	ds_read_b128 v[176:179], v211 offset:20480
	ds_read_b128 v[180:183], v211 offset:21504
	ds_read_b128 v[184:187], v211 offset:22528
	ds_read_b128 v[188:191], v211 offset:23552
	s_mov_b32 s5, m0
	s_mov_b32 m0, s73
	s_nop 0
	global_load_lds_dwordx4 v217, s[68:69]
	s_mov_b32 m0, s5
	s_add_u32 s6, s68, 0x40000
	s_mov_b32 s5, m0
	s_mov_b32 m0, s74
	s_nop 0
	global_load_lds_dwordx4 v248, s[68:69]
	s_mov_b32 m0, s5
	s_addc_u32 s7, s69, 0
	s_mov_b32 s5, m0
	s_mov_b32 m0, s75
	s_nop 0
	global_load_lds_dwordx4 v217, s[6:7]
	s_mov_b32 m0, s5
	s_nop 0
	s_mov_b32 s5, m0
	s_mov_b32 m0, s80
	s_nop 0
	global_load_lds_dwordx4 v248, s[6:7]
	s_mov_b32 m0, s5
	s_nop 0
	s_mov_b32 s5, m0
	s_mov_b32 m0, s72
	s_nop 0
	global_load_lds_dwordx4 v250, s[62:63]
	s_mov_b32 m0, s5
	s_nop 0
	s_mov_b32 s5, m0
	s_mov_b32 m0, s81
	s_nop 0
	global_load_lds_dwordx4 v247, s[62:63]
	s_mov_b32 m0, s5
	s_waitcnt vmcnt(8)
	s_waitcnt lgkmcnt(0)
	s_barrier
; #define PG8_STAGE(bufoff, gbase, voff) do { _Pragma("unroll") for (int _i = 0; _i < 2; ++_i) glds16_s((gbase), (voff)[_i], ldsb + (unsigned)((bufoff) + _i * 8192)); } while (0)
; #define PG8_LDA(dst, b, h) do { _Pragma("unroll") for (int m = 0; m < 4; ++m) _Pragma("unroll") for (int k = 0; k < 2; ++k) dst[m][k] = *(const LAS h16x8*)(lds + PG8_SA(b, h) + aoff + m * 2048 + k * 1024); } while (0)
; #define PG8_LDB(dst, b, h) do { _Pragma("unroll") for (int n = 0; n < 2; ++n) _Pragma("unroll") for (int k = 0; k < 2; ++k) dst[n][k] = *(const LAS h16x8*)(lds + PG8_SB(b, h) + boff + n * 2048 + k * 1024); } while (0)
; #define PG8_MMA(ai, bj, At, Bt) do { __builtin_amdgcn_s_setprio(1); _Pragma("unroll") for (int m = 0; m < 4; ++m) _Pragma("unroll") for (int n = 0; n < 2; ++n) _Pragma("unroll") for (int k = 0; k < 2; ++k) \
;         acc[ai][bj][m][n] = mma_step<I8>(Bt[n][k], At[m][k], acc[ai][bj][m][n]); __builtin_amdgcn_s_setprio(0); } while (0)
; #define PG8_WAIT_V(n) asm volatile("s_waitcnt vmcnt(" #n ")" ::: "memory")
; #define PG8_WAIT_L(n) asm volatile("s_waitcnt lgkmcnt(" #n ")" ::: "memory")
; #define PG8_BAR __builtin_amdgcn_s_barrier()
; #define PG8_SCHED __builtin_amdgcn_sched_barrier(0)
; template <class Prob, class Epi, bool I8 = false, bool ALIGN_EPI = true, bool SP2 = true>
; __device__ __forceinline__ void gemm_phase(LAS unsigned char* lds, int wave, const Prob& P, const Epi& E) {
;     ...
;             PG8_WAIT_V(8); PG8_WAIT_L(0); PG8_BAR; PG8_MMA(1, 0, At, B0); PG8_MMA(1, 1, At, B1); PG8_BAR; PG8_SCHED;
;             PG8_LDB(B0, 1, 0); PG8_LDB(B1, 1, 1); PG8_SCHED; PG8_LDA(At, 1, 0); PG8_STAGE(PG8_SA(0, 1), a2 + hstepA, voffA);
;             PG8_WAIT_V(8); PG8_WAIT_L(0); PG8_BAR; PG8_MMA(0, 0, At, B0); PG8_MMA(0, 1, At, B1); PG8_BAR; PG8_SCHED;
	s_setprio 1
	s_waitcnt lgkmcnt(7)
	v_mfma_i32_16x16x64_i8 v[40:43], v[104:107], v[144:147], v[40:43]
	v_mfma_i32_16x16x64_i8 v[64:67], v[120:123], v[144:147], v[64:67]
	s_waitcnt lgkmcnt(5)
	v_mfma_i32_16x16x64_i8 v[36:39], v[104:107], v[168:171], v[36:39]
	v_mfma_i32_16x16x64_i8 v[60:63], v[120:123], v[168:171], v[60:63]
	s_waitcnt lgkmcnt(3)
	v_mfma_i32_16x16x64_i8 v[32:35], v[104:107], v[176:179], v[32:35]
	v_mfma_i32_16x16x64_i8 v[56:59], v[120:123], v[176:179], v[56:59]
	s_waitcnt lgkmcnt(1)
	v_mfma_i32_16x16x64_i8 v[104:107], v[104:107], v[184:187], v[156:159]
	v_mfma_i32_16x16x64_i8 v[40:43], v[112:115], v[164:167], v[40:43]
	v_mfma_i32_16x16x64_i8 v[64:67], v[124:127], v[164:167], v[64:67]
	v_mfma_i32_16x16x64_i8 v[36:39], v[112:115], v[172:175], v[36:39]
	v_mfma_i32_16x16x64_i8 v[60:63], v[124:127], v[172:175], v[60:63]
	v_mfma_i32_16x16x64_i8 v[32:35], v[112:115], v[180:183], v[32:35]
	v_mfma_i32_16x16x64_i8 v[56:59], v[124:127], v[180:183], v[56:59]
	s_waitcnt lgkmcnt(0)
	v_mfma_i32_16x16x64_i8 v[104:107], v[112:115], v[188:191], v[104:107]
	v_mfma_i32_16x16x64_i8 v[112:115], v[120:123], v[184:187], v[148:151]
	v_mfma_i32_16x16x64_i8 v[112:115], v[124:127], v[188:191], v[112:115]
	s_setprio 0
	s_setprio 1
	v_mfma_i32_16x16x64_i8 v[88:91], v[128:131], v[144:147], v[88:91]
	v_mfma_i32_16x16x64_i8 v[12:15], v[136:139], v[144:147], v[12:15]
	v_mfma_i32_16x16x64_i8 v[84:87], v[128:131], v[168:171], v[84:87]
	v_mfma_i32_16x16x64_i8 v[8:11], v[136:139], v[168:171], v[8:11]
	v_mfma_i32_16x16x64_i8 v[76:79], v[128:131], v[176:179], v[76:79]
	v_mfma_i32_16x16x64_i8 v[4:7], v[136:139], v[176:179], v[4:7]
	v_mfma_i32_16x16x64_i8 v[108:111], v[128:131], v[184:187], v[108:111]
	v_mfma_i32_16x16x64_i8 v[0:3], v[136:139], v[184:187], v[0:3]
	v_mfma_i32_16x16x64_i8 v[88:91], v[132:135], v[164:167], v[88:91]
	v_mfma_i32_16x16x64_i8 v[12:15], v[140:143], v[164:167], v[12:15]
	v_mfma_i32_16x16x64_i8 v[84:87], v[132:135], v[172:175], v[84:87]
	v_mfma_i32_16x16x64_i8 v[8:11], v[140:143], v[172:175], v[8:11]
	v_mfma_i32_16x16x64_i8 v[76:79], v[132:135], v[180:183], v[76:79]
	v_mfma_i32_16x16x64_i8 v[4:7], v[140:143], v[180:183], v[4:7]
	v_mfma_i32_16x16x64_i8 v[108:111], v[132:135], v[188:191], v[108:111]
	v_mfma_i32_16x16x64_i8 v[0:3], v[140:143], v[188:191], v[0:3]
	s_setprio 0
	s_barrier
	v_add_u32_e32 v132, 0x18000, v210
	v_add_u32_e32 v148, 0x1c000, v210
	ds_read_b128 v[120:123], v132
	ds_read_b128 v[124:127], v132 offset:1024
	ds_read_b128 v[128:131], v132 offset:2048
	ds_read_b128 v[132:135], v132 offset:3072
	ds_read_b128 v[136:139], v148
	ds_read_b128 v[140:143], v148 offset:1024
	ds_read_b128 v[144:147], v148 offset:2048
	ds_read_b128 v[164:167], v148 offset:3072
	ds_read_b128 v[148:151], v211 offset:32768
	ds_read_b128 v[156:159], v211 offset:33792
	ds_read_b128 v[168:171], v211 offset:34816
	ds_read_b128 v[172:175], v211 offset:35840
	ds_read_b128 v[176:179], v211 offset:36864
	ds_read_b128 v[180:183], v211 offset:37888
	ds_read_b128 v[184:187], v211 offset:38912
	ds_read_b128 v[188:191], v211 offset:39936
	s_add_u32 s6, s62, 0x2000
	s_addc_u32 s7, s63, 0
	s_mov_b32 s5, m0
	s_mov_b32 m0, s82
	s_nop 0
	global_load_lds_dwordx4 v250, s[6:7]
	s_mov_b32 m0, s5
	s_nop 0
	s_mov_b32 s5, m0
	s_mov_b32 m0, s83
	s_nop 0
	global_load_lds_dwordx4 v247, s[6:7]
	s_mov_b32 m0, s5
	s_waitcnt vmcnt(8)
	s_waitcnt lgkmcnt(0)
	s_barrier
	s_setprio 1
	s_waitcnt lgkmcnt(7)
	v_mfma_i32_16x16x64_i8 v[160:163], v[120:123], v[148:151], v[160:163]
	v_mfma_i32_16x16x64_i8 v[152:155], v[128:131], v[148:151], v[152:155]
	s_waitcnt lgkmcnt(5)
	v_mfma_i32_16x16x64_i8 v[52:55], v[120:123], v[168:171], v[52:55]
	v_mfma_i32_16x16x64_i8 v[80:83], v[128:131], v[168:171], v[80:83]
	s_waitcnt lgkmcnt(3)
	v_mfma_i32_16x16x64_i8 v[48:51], v[120:123], v[176:179], v[48:51]
	v_mfma_i32_16x16x64_i8 v[72:75], v[128:131], v[176:179], v[72:75]
	s_waitcnt lgkmcnt(1)
	v_mfma_i32_16x16x64_i8 v[44:47], v[120:123], v[184:187], v[44:47]
	v_mfma_i32_16x16x64_i8 v[68:71], v[128:131], v[184:187], v[68:71]
	v_mfma_i32_16x16x64_i8 v[160:163], v[124:127], v[156:159], v[160:163]
	v_mfma_i32_16x16x64_i8 v[152:155], v[132:135], v[156:159], v[152:155]
	v_mfma_i32_16x16x64_i8 v[52:55], v[124:127], v[172:175], v[52:55]
	v_mfma_i32_16x16x64_i8 v[80:83], v[132:135], v[172:175], v[80:83]
	v_mfma_i32_16x16x64_i8 v[48:51], v[124:127], v[180:183], v[48:51]
	v_mfma_i32_16x16x64_i8 v[72:75], v[132:135], v[180:183], v[72:75]
	s_waitcnt lgkmcnt(0)
	v_mfma_i32_16x16x64_i8 v[44:47], v[124:127], v[188:191], v[44:47]
	v_mfma_i32_16x16x64_i8 v[68:71], v[132:135], v[188:191], v[68:71]
	s_setprio 0
	s_setprio 1
	v_mfma_i32_16x16x64_i8 v[116:119], v[136:139], v[148:151], v[116:119]
	v_mfma_i32_16x16x64_i8 v[28:31], v[144:147], v[148:151], v[28:31]
	v_mfma_i32_16x16x64_i8 v[100:103], v[136:139], v[168:171], v[100:103]
	v_mfma_i32_16x16x64_i8 v[24:27], v[144:147], v[168:171], v[24:27]
	v_mfma_i32_16x16x64_i8 v[96:99], v[136:139], v[176:179], v[96:99]
	v_mfma_i32_16x16x64_i8 v[20:23], v[144:147], v[176:179], v[20:23]
	v_mfma_i32_16x16x64_i8 v[92:95], v[136:139], v[184:187], v[92:95]
	v_mfma_i32_16x16x64_i8 v[16:19], v[144:147], v[184:187], v[16:19]
	v_mfma_i32_16x16x64_i8 v[116:119], v[140:143], v[156:159], v[116:119]
	v_mfma_i32_16x16x64_i8 v[28:31], v[164:167], v[156:159], v[28:31]
	v_mfma_i32_16x16x64_i8 v[100:103], v[140:143], v[172:175], v[100:103]
	v_mfma_i32_16x16x64_i8 v[24:27], v[164:167], v[172:175], v[24:27]
	v_mfma_i32_16x16x64_i8 v[96:99], v[140:143], v[180:183], v[96:99]
	v_mfma_i32_16x16x64_i8 v[20:23], v[164:167], v[180:183], v[20:23]
	v_mfma_i32_16x16x64_i8 v[92:95], v[140:143], v[188:191], v[92:95]
	v_mfma_i32_16x16x64_i8 v[16:19], v[164:167], v[188:191], v[16:19]
	s_setprio 0
	s_barrier
; #define PG8_STAGE(bufoff, gbase, voff) do { _Pragma("unroll") for (int _i = 0; _i < 2; ++_i) glds16_s((gbase), (voff)[_i], ldsb + (unsigned)((bufoff) + _i * 8192)); } while (0)
; #define PG8_LDA(dst, b, h) do { _Pragma("unroll") for (int m = 0; m < 4; ++m) _Pragma("unroll") for (int k = 0; k < 2; ++k) dst[m][k] = *(const LAS h16x8*)(lds + PG8_SA(b, h) + aoff + m * 2048 + k * 1024); } while (0)
; #define PG8_MMA(ai, bj, At, Bt) do { __builtin_amdgcn_s_setprio(1); _Pragma("unroll") for (int m = 0; m < 4; ++m) _Pragma("unroll") for (int n = 0; n < 2; ++n) _Pragma("unroll") for (int k = 0; k < 2; ++k) \
;         acc[ai][bj][m][n] = mma_step<I8>(Bt[n][k], At[m][k], acc[ai][bj][m][n]); __builtin_amdgcn_s_setprio(0); } while (0)
; #define PG8_WAIT_V(n) asm volatile("s_waitcnt vmcnt(" #n ")" ::: "memory")
; #define PG8_WAIT_L(n) asm volatile("s_waitcnt lgkmcnt(" #n ")" ::: "memory")
; #define PG8_BAR __builtin_amdgcn_s_barrier()
; #define PG8_SCHED __builtin_amdgcn_sched_barrier(0)
; template <class Prob, class Epi, bool I8 = false, bool ALIGN_EPI = true, bool SP2 = true>
; __device__ __forceinline__ void gemm_phase(LAS unsigned char* lds, int wave, const Prob& P, const Epi& E) {
;     ...
;             PG8_LDA(At, 1, 1); PG8_STAGE(PG8_SB(1, 0), b3, voffB); PG8_STAGE(PG8_SB(1, 1), b3 + hstepB, voffB); PG8_STAGE(PG8_SA(1, 0), a3, voffA);
;             PG8_WAIT_V(8); PG8_WAIT_L(0); PG8_BAR; PG8_MMA(1, 0, At, B0); PG8_MMA(1, 1, At, B1); PG8_BAR; PG8_SCHED;
	ds_read_b128 v[168:171], v211 offset:49152
	ds_read_b128 v[172:175], v211 offset:50176
	ds_read_b128 v[176:179], v211 offset:51200
	ds_read_b128 v[180:183], v211 offset:52224
	ds_read_b128 v[184:187], v211 offset:53248
	ds_read_b128 v[188:191], v211 offset:54272
	ds_read_b128 v[192:195], v211 offset:55296
	ds_read_b128 v[196:199], v211 offset:56320
	s_add_u32 s6, s68, 0x80
	s_addc_u32 s7, s69, 0
	s_mov_b32 s5, m0
	s_mov_b32 m0, s2
	s_nop 0
	global_load_lds_dwordx4 v217, s[6:7]
	s_mov_b32 m0, s5
	s_nop 0
	s_mov_b32 s5, m0
	s_mov_b32 m0, s85
	s_nop 0
	global_load_lds_dwordx4 v248, s[6:7]
	s_mov_b32 m0, s5
	s_add_u32 s6, s68, 0x40080
	s_addc_u32 s7, s69, 0
	s_mov_b32 s5, m0
	s_mov_b32 m0, s88
	s_nop 0
	global_load_lds_dwordx4 v217, s[6:7]
	s_mov_b32 m0, s5
	s_nop 0
	s_mov_b32 s5, m0
	s_mov_b32 m0, s89
	s_nop 0
	global_load_lds_dwordx4 v248, s[6:7]
	s_mov_b32 m0, s5
	s_nop 0
	s_mov_b32 s5, m0
	s_mov_b32 m0, s86
	s_nop 0
	global_load_lds_dwordx4 v250, s[60:61]
	s_mov_b32 m0, s5
	s_nop 0
	s_mov_b32 s5, m0
	s_mov_b32 m0, s87
	s_nop 0
	global_load_lds_dwordx4 v247, s[60:61]
	s_mov_b32 m0, s5
	s_waitcnt vmcnt(8)
	s_waitcnt lgkmcnt(0)
	s_barrier
	s_setprio 1
	s_waitcnt lgkmcnt(1)
	v_mfma_i32_16x16x64_i8 v[104:107], v[120:123], v[192:195], v[104:107]
	v_mfma_i32_16x16x64_i8 v[40:43], v[120:123], v[168:171], v[40:43]
	v_mfma_i32_16x16x64_i8 v[64:67], v[128:131], v[168:171], v[64:67]
	v_mfma_i32_16x16x64_i8 v[36:39], v[120:123], v[176:179], v[36:39]
	v_mfma_i32_16x16x64_i8 v[60:63], v[128:131], v[176:179], v[60:63]
	v_mfma_i32_16x16x64_i8 v[32:35], v[120:123], v[184:187], v[32:35]
	v_mfma_i32_16x16x64_i8 v[56:59], v[128:131], v[184:187], v[56:59]
	s_waitcnt lgkmcnt(0)
	v_mfma_i32_16x16x64_i8 v[156:159], v[124:127], v[196:199], v[104:107]
	v_mfma_i32_16x16x64_i8 v[104:107], v[128:131], v[192:195], v[112:115]
	v_mfma_i32_16x16x64_i8 v[40:43], v[124:127], v[172:175], v[40:43]
	v_mfma_i32_16x16x64_i8 v[64:67], v[132:135], v[172:175], v[64:67]
	v_mfma_i32_16x16x64_i8 v[36:39], v[124:127], v[180:183], v[36:39]
	v_mfma_i32_16x16x64_i8 v[60:63], v[132:135], v[180:183], v[60:63]
	v_mfma_i32_16x16x64_i8 v[32:35], v[124:127], v[188:191], v[32:35]
	v_mfma_i32_16x16x64_i8 v[56:59], v[132:135], v[188:191], v[56:59]
	v_mfma_i32_16x16x64_i8 v[148:151], v[132:135], v[196:199], v[104:107]
	s_setprio 0
	s_setprio 1
	v_mfma_i32_16x16x64_i8 v[88:91], v[136:139], v[168:171], v[88:91]
	v_mfma_i32_16x16x64_i8 v[12:15], v[144:147], v[168:171], v[12:15]
	v_mfma_i32_16x16x64_i8 v[84:87], v[136:139], v[176:179], v[84:87]
	v_mfma_i32_16x16x64_i8 v[8:11], v[144:147], v[176:179], v[8:11]
	v_mfma_i32_16x16x64_i8 v[76:79], v[136:139], v[184:187], v[76:79]
	v_mfma_i32_16x16x64_i8 v[4:7], v[144:147], v[184:187], v[4:7]
	v_mfma_i32_16x16x64_i8 v[104:107], v[136:139], v[192:195], v[108:111]
	v_mfma_i32_16x16x64_i8 v[0:3], v[144:147], v[192:195], v[0:3]
	v_mfma_i32_16x16x64_i8 v[88:91], v[140:143], v[172:175], v[88:91]
	v_mfma_i32_16x16x64_i8 v[12:15], v[164:167], v[172:175], v[12:15]
	v_mfma_i32_16x16x64_i8 v[84:87], v[140:143], v[180:183], v[84:87]
	v_mfma_i32_16x16x64_i8 v[8:11], v[164:167], v[180:183], v[8:11]
	v_mfma_i32_16x16x64_i8 v[76:79], v[140:143], v[188:191], v[76:79]
	v_mfma_i32_16x16x64_i8 v[4:7], v[164:167], v[188:191], v[4:7]
	v_mfma_i32_16x16x64_i8 v[108:111], v[140:143], v[196:199], v[104:107]
	v_mfma_i32_16x16x64_i8 v[0:3], v[164:167], v[196:199], v[0:3]
	s_setprio 0
	s_barrier
	s_add_i32 s4, s4, 2
	s_add_u32 vcc_lo, vcc_lo, 0x100
	s_addc_u32 vcc_hi, vcc_hi, 0
	s_add_u32 s0, s0, 0x100
	s_addc_u32 s1, s1, 0
	s_add_u32 s44, s44, 0x100
	s_addc_u32 s45, s45, 0
	s_cmp_gt_u32 s4, 13
	s_cbranch_scc0 .LBB0_1065
	s_mov_b32 s100, 0xbfb8aa3b
	s_mov_b32 s101, 0
	s_and_b64 vcc, exec, s[46:47]
	s_cbranch_vccz .LBB0_1068
	s_barrier

;     __device__ bool next(int i, Unit& u) const { return S.next(i, u); }
;     __device__ __forceinline__ void operator()(Acc& acc, const Unit& u, int wr, int wc, int fr, int fq, LAS unsigned char* lds, int tid) const {
;     ...
;         if constexpr (I8) {
; #pragma unroll
;             for (int ai = 0; ai < 2; ++ai) { const f32x4 sa = ldf4(sx, tok0 + tl0 + 4u * ai);
; #pragma unroll
;                 for (int m = 0; m < 4; ++m)
; #pragma unroll
;                     for (int bj = 0; bj < 2; ++bj)
; #pragma unroll
;                         for (int n = 0; n < 2; ++n) { const pg8::i32x4 iv = __builtin_bit_cast(pg8::i32x4, acc[ai][bj][m][n]); acc[ai][bj][m][n] = __builtin_convertvector(iv, f32x4) * sa[m]; }
;                 asm volatile("" ::: "memory"); }
;         }
;         const unsigned bk = 2 * u.pm + wr;
;         const bool lvalid = (bk & 15) != 0, rvalid = (bk & 15) != 15;
; #pragma unroll
;         for (int bj = 0; bj < 2; ++bj) {
;             const unsigned colp = u.pn * 256 + bj * 128 + wc * 32 + 8 * fq;
;             const unsigned coll = bj * FF + u.pn * 128 + wc * 32 + 8 * fq;
; #pragma unroll
;             for (int n = 0; n < 2; ++n) {
;                 f32x4 c0 = ldf4(cw, coll + 4u * n), c1 = ldf4(cw, (unsigned)FF2 + coll + 4u * n), c2 = ldf4(cw, 2u * FF2 + coll + 4u * n);
;                 if constexpr (I8) { const f32x4 swv = ldf4(sw, colp + 4u * n); c0 = c0 * swv; c1 = c1 * swv; c2 = c2 * swv; }
;                 f32x4 hl = {0.f, 0.f, 0.f, 0.f}, hr = {0.f, 0.f, 0.f, 0.f};
;                 if (fr == 0 && lvalid) hl = ldf4(HALO, (2u * bk) * (unsigned)FF2 + colp + 4u * n);
;                 if (fr == 15 && rvalid) hr = ldf4(HALO, (2u * bk + 1u) * (unsigned)FF2 + colp + 4u * n);
; #pragma unroll
;                 for (int e = 0; e < 4; ++e) {
;                     const float prev = dpp_shr1(hl[e], acc[1][bj][3][n][e]);
;                     const float next = dpp_shl1(hr[e], acc[0][bj][0][n][e]);
;                     float left = prev;
; #pragma unroll
;                     for (int j = 0; j < 8; ++j) {
;                         const float cur = acc[j >> 2][bj][j & 3][n][e];
;                         const float nx = (j < 7) ? acc[(j + 1) >> 2][bj][(j + 1) & 3][n][e] : next;
;                         acc[j >> 2][bj][j & 3][n][e] = c0[e] * left + c1[e] * cur + c2[e] * nx;
.LBB0_1084:
	s_or_b64 exec, exec, s[44:45]
	v_cvt_f32_i32_e32 v53, v53
	v_cvt_f32_i32_e32 v52, v52
	v_cvt_f32_i32_e32 v49, v49
	v_cvt_f32_i32_e32 v48, v48
	v_pk_mul_f32 v[136:137], v[136:137], v[132:133]
	v_pk_mul_f32 v[140:141], v[140:141], v[132:133]
	v_pk_mul_f32 v[120:121], v[136:137], v[120:121]
	v_pk_mul_f32 v[52:53], v[112:113], v[52:53] op_sel:[1,0]
	v_cvt_f32_i32_e32 v45, v45
	v_cvt_f32_i32_e32 v44, v44
	v_pk_mul_f32 v[138:139], v[138:139], v[134:135]
	v_pk_mul_f32 v[142:143], v[142:143], v[134:135]
	v_pk_mul_f32 v[134:135], v[130:131], v[134:135]
	v_pk_mul_f32 v[130:131], v[128:129], v[132:133]
	v_pk_fma_f32 v[120:121], v[224:225], v[140:141], v[120:121]
	v_cvt_f32_i32_e32 v41, v41
	v_cvt_f32_i32_e32 v40, v40
	v_pk_fma_f32 v[132:133], v[52:53], v[130:131], v[120:121]
	v_pk_mul_f32 v[120:121], v[52:53], v[140:141]
	v_pk_mul_f32 v[48:49], v[114:115], v[48:49] op_sel_hi:[0,1]
	v_cvt_f32_i32_e32 v37, v37
	v_cvt_f32_i32_e32 v36, v36
	v_pk_fma_f32 v[120:121], v[224:225], v[136:137], v[120:121]
	v_mov_b32_e32 v208, v115
	v_cvt_f32_i32_e32 v33, v33
	v_cvt_f32_i32_e32 v32, v32
	v_pk_fma_f32 v[128:129], v[48:49], v[130:131], v[120:121]
	v_pk_mul_f32 v[120:121], v[48:49], v[140:141]
	v_pk_mul_f32 v[44:45], v[208:209], v[44:45] op_sel_hi:[0,1]
	v_pk_fma_f32 v[52:53], v[52:53], v[136:137], v[120:121]
	v_pk_mul_f32 v[40:41], v[104:105], v[40:41] op_sel_hi:[0,1]
	v_pk_fma_f32 v[120:121], v[44:45], v[130:131], v[52:53]
	v_pk_mul_f32 v[52:53], v[44:45], v[140:141]
	v_cvt_f32_i32_e32 v55, v55
	v_cvt_f32_i32_e32 v54, v54
	v_pk_mul_f32 v[36:37], v[104:105], v[36:37] op_sel:[1,0]
	v_pk_fma_f32 v[48:49], v[48:49], v[136:137], v[52:53]
	v_pk_mul_f32 v[52:53], v[40:41], v[140:141]
	v_pk_mul_f32 v[32:33], v[106:107], v[32:33] op_sel_hi:[0,1]
	v_pk_fma_f32 v[44:45], v[44:45], v[136:137], v[52:53]
	v_pk_mul_f32 v[52:53], v[36:37], v[140:141]
	v_cvt_f32_i32_e32 v51, v51
	v_cvt_f32_i32_e32 v50, v50
	v_pk_fma_f32 v[48:49], v[40:41], v[130:131], v[48:49]
	v_pk_fma_f32 v[40:41], v[40:41], v[136:137], v[52:53]
	v_pk_mul_f32 v[52:53], v[32:33], v[140:141]
	v_pk_fma_f32 v[44:45], v[36:37], v[130:131], v[44:45]
	v_pk_fma_f32 v[36:37], v[36:37], v[136:137], v[52:53]
	v_pk_mul_f32 v[52:53], v[138:139], v[122:123]
	v_pk_mul_f32 v[54:55], v[112:113], v[54:55] op_sel:[1,0]
	v_cvt_f32_i32_e32 v47, v47
	v_cvt_f32_i32_e32 v46, v46
	v_pk_fma_f32 v[52:53], v[220:221], v[142:143], v[52:53]
	v_cvt_f32_i32_e32 v43, v43
	v_cvt_f32_i32_e32 v42, v42
	v_pk_fma_f32 v[40:41], v[32:33], v[130:131], v[40:41]
	v_pk_mul_f32 v[32:33], v[32:33], v[136:137]
	v_pk_fma_f32 v[136:137], v[54:55], v[134:135], v[52:53]
	v_pk_mul_f32 v[52:53], v[54:55], v[142:143]
	v_pk_mul_f32 v[50:51], v[114:115], v[50:51] op_sel_hi:[0,1]
	v_cvt_f32_i32_e32 v39, v39
	v_cvt_f32_i32_e32 v38, v38
	v_pk_fma_f32 v[32:33], v[222:223], v[140:141], v[32:33]
	v_pk_fma_f32 v[52:53], v[220:221], v[138:139], v[52:53]
	v_pk_fma_f32 v[36:37], v[222:223], v[130:131], v[36:37]
	v_pk_fma_f32 v[32:33], v[130:131], v[124:125], v[32:33]
	v_pk_fma_f32 v[130:131], v[50:51], v[134:135], v[52:53]
	v_pk_mul_f32 v[52:53], v[50:51], v[142:143]
	v_cvt_f32_i32_e32 v27, v27
	v_cvt_f32_i32_e32 v26, v26
	v_cvt_f32_i32_e32 v13, v13
	v_cvt_f32_i32_e32 v12, v12
	v_pk_mul_f32 v[46:47], v[208:209], v[46:47] op_sel_hi:[0,1]
	v_cvt_f32_i32_e32 v35, v35
	v_cvt_f32_i32_e32 v34, v34
	v_pk_fma_f32 v[52:53], v[54:55], v[138:139], v[52:53]
	v_cvt_f32_i32_e32 v101, v101
	v_cvt_f32_i32_e32 v100, v100
	v_cvt_f32_i32_e32 v97, v97
	v_cvt_f32_i32_e32 v96, v96
	v_pk_mul_f32 v[42:43], v[104:105], v[42:43] op_sel_hi:[0,1]
	v_pk_fma_f32 v[122:123], v[46:47], v[134:135], v[52:53]
	v_pk_mul_f32 v[52:53], v[46:47], v[142:143]
	v_cvt_f32_i32_e32 v93, v93
	v_cvt_f32_i32_e32 v92, v92
	v_pk_mul_f32 v[38:39], v[104:105], v[38:39] op_sel:[1,0]
	v_pk_fma_f32 v[50:51], v[50:51], v[138:139], v[52:53]
	v_pk_mul_f32 v[52:53], v[42:43], v[142:143]
	v_cvt_f32_i32_e32 v11, v11
	v_cvt_f32_i32_e32 v10, v10
	v_cvt_f32_i32_e32 v89, v89
	v_cvt_f32_i32_e32 v88, v88
	v_pk_mul_f32 v[214:215], v[190:191], v[202:203]
	v_pk_mul_f32 v[190:191], v[188:189], v[200:201]
	v_pk_fma_f32 v[46:47], v[46:47], v[138:139], v[52:53]
	v_pk_mul_f32 v[52:53], v[38:39], v[142:143]
	v_cvt_f32_i32_e32 v31, v31
	v_cvt_f32_i32_e32 v30, v30
	v_pk_mul_f32 v[124:125], v[112:113], v[26:27] op_sel:[1,0]
	v_cvt_f32_i32_e32 v17, v17
	v_cvt_f32_i32_e32 v16, v16
	v_pk_mul_f32 v[26:27], v[104:105], v[12:13] op_sel_hi:[0,1]
	v_cvt_f32_i32_e32 v13, v9
	v_cvt_f32_i32_e32 v12, v8
	v_cvt_f32_i32_e32 v85, v85
	v_cvt_f32_i32_e32 v84, v84
	v_pk_mul_f32 v[196:197], v[196:197], v[200:201]
	v_pk_mul_f32 v[176:177], v[190:191], v[176:177]
	v_pk_mul_f32 v[34:35], v[106:107], v[34:35] op_sel_hi:[0,1]
	v_pk_fma_f32 v[50:51], v[42:43], v[134:135], v[50:51]
	v_pk_fma_f32 v[42:43], v[42:43], v[138:139], v[52:53]
	v_pk_mul_f32 v[100:101], v[112:113], v[100:101] op_sel:[1,0]
	v_pk_mul_f32 v[96:97], v[114:115], v[96:97] op_sel_hi:[0,1]
	v_pk_mul_f32 v[192:193], v[192:193], v[200:201]
	v_pk_fma_f32 v[176:177], v[244:245], v[196:197], v[176:177]
	v_pk_fma_f32 v[42:43], v[34:35], v[134:135], v[42:43]
	v_pk_mul_f32 v[52:53], v[34:35], v[142:143]
	v_pk_mul_f32 v[34:35], v[34:35], v[138:139]
	v_pk_mul_f32 v[92:93], v[208:209], v[92:93] op_sel_hi:[0,1]
	v_cvt_f32_i32_e32 v77, v77
	v_cvt_f32_i32_e32 v79, v79
	v_cvt_f32_i32_e32 v78, v78
	v_cvt_f32_i32_e32 v76, v76
	v_pk_fma_f32 v[188:189], v[100:101], v[192:193], v[176:177]
	v_pk_mul_f32 v[176:177], v[100:101], v[196:197]
	v_pk_mul_f32 v[200:201], v[96:97], v[196:197]
	v_cvt_f32_i32_e32 v57, v57
	v_cvt_f32_i32_e32 v59, v59
	v_cvt_f32_i32_e32 v58, v58
	v_cvt_f32_i32_e32 v56, v56
;     __device__ bool next(int i, Unit& u) const { return S.next(i, u); }
; __device__ __forceinline__ float silu_f(float x) { return x * __builtin_amdgcn_rcpf(1.0f + __expf(-x)); }
;     __device__ __forceinline__ void operator()(Acc& acc, const Unit& u, int wr, int wc, int fr, int fq, LAS unsigned char* lds, int tid) const {
;     ...
;         for (int bj = 0; bj < 2; ++bj) {
;             const unsigned colp = u.pn * 256 + bj * 128 + wc * 32 + 8 * fq;
;             const unsigned coll = bj * FF + u.pn * 128 + wc * 32 + 8 * fq;
; #pragma unroll
;             for (int n = 0; n < 2; ++n) {
;                 f32x4 c0 = ldf4(cw, coll + 4u * n), c1 = ldf4(cw, (unsigned)FF2 + coll + 4u * n), c2 = ldf4(cw, 2u * FF2 + coll + 4u * n);
;                 if constexpr (I8) { const f32x4 swv = ldf4(sw, colp + 4u * n); c0 = c0 * swv; c1 = c1 * swv; c2 = c2 * swv; }
;                 f32x4 hl = {0.f, 0.f, 0.f, 0.f}, hr = {0.f, 0.f, 0.f, 0.f};
;                 if (fr == 0 && lvalid) hl = ldf4(HALO, (2u * bk) * (unsigned)FF2 + colp + 4u * n);
;                 if (fr == 15 && rvalid) hr = ldf4(HALO, (2u * bk + 1u) * (unsigned)FF2 + colp + 4u * n);
; #pragma unroll
;                 for (int e = 0; e < 4; ++e) {
;                     const float prev = dpp_shr1(hl[e], acc[1][bj][3][n][e]);
;                     const float next = dpp_shl1(hr[e], acc[0][bj][0][n][e]);
;                     float left = prev;
; #pragma unroll
;                     for (int j = 0; j < 8; ++j) {
;                         const float cur = acc[j >> 2][bj][j & 3][n][e];
;                         const float nx = (j < 7) ? acc[(j + 1) >> 2][bj][(j + 1) & 3][n][e] : next;
;                         acc[j >> 2][bj][j & 3][n][e] = c0[e] * left + c1[e] * cur + c2[e] * nx;
;                         left = cur;
;                     }
;                 }
;                 asm volatile("" ::: "memory");
;             }
;         }
;         const unsigned colo = u.pn * 128 + wc * 32 + 8 * fq;
; #pragma unroll
;         for (int ai = 0; ai < 2; ++ai)
; #pragma unroll
;             for (int m = 0; m < 4; ++m) {
;                 f32x4 a[2];
; #pragma unroll
;                 for (int n = 0; n < 2; ++n)
; #pragma unroll
;                     for (int e = 0; e < 4; ++e) a[n][e] = silu_f(acc[ai][0][m][n][e]) * acc[ai][1][m][n][e];
	v_pk_fma_f32 v[46:47], v[38:39], v[134:135], v[46:47]
	v_pk_fma_f32 v[38:39], v[38:39], v[138:139], v[52:53]
	v_pk_fma_f32 v[34:35], v[218:219], v[142:143], v[34:35]
	v_mov_b32_e32 v52, v112
	v_mov_b32_e32 v53, v112
	v_pk_mul_f32 v[8:9], v[104:105], v[10:11] op_sel:[1,0]
	v_cvt_f32_i32_e32 v7, v7
	v_cvt_f32_i32_e32 v6, v6
	v_cvt_f32_i32_e32 v11, v5
	v_cvt_f32_i32_e32 v10, v4
	v_pk_mul_f32 v[88:89], v[104:105], v[88:89] op_sel_hi:[0,1]
	v_pk_fma_f32 v[176:177], v[244:245], v[190:191], v[176:177]
	v_pk_fma_f32 v[100:101], v[100:101], v[190:191], v[200:201]
	v_pk_mul_f32 v[200:201], v[92:93], v[196:197]
	v_pk_fma_f32 v[34:35], v[134:135], v[126:127], v[34:35]
	v_pk_mul_f32 v[126:127], v[52:53], v[30:31]
	v_pk_mul_f32 v[30:31], v[208:209], v[16:17] op_sel_hi:[0,1]
	v_pk_mul_f32 v[16:17], v[104:105], v[12:13] op_sel:[1,0]
	v_cvt_f32_i32_e32 v13, v3
	v_cvt_f32_i32_e32 v12, v2
	v_cvt_f32_i32_e32 v103, v103
	v_cvt_f32_i32_e32 v102, v102
	v_cvt_f32_i32_e32 v99, v99
	v_cvt_f32_i32_e32 v98, v98
	v_pk_mul_f32 v[84:85], v[104:105], v[84:85] op_sel:[1,0]
	v_pk_fma_f32 v[176:177], v[96:97], v[192:193], v[176:177]
	v_pk_fma_f32 v[96:97], v[96:97], v[190:191], v[200:201]
	v_pk_mul_f32 v[200:201], v[88:89], v[196:197]
	v_cvt_f32_i32_e32 v95, v95
	v_cvt_f32_i32_e32 v94, v94
	v_pk_fma_f32 v[100:101], v[92:93], v[192:193], v[100:101]
	v_pk_fma_f32 v[92:93], v[92:93], v[190:191], v[200:201]
	v_pk_mul_f32 v[200:201], v[84:85], v[196:197]
	v_cvt_f32_i32_e32 v91, v91
	v_cvt_f32_i32_e32 v90, v90
	v_pk_mul_f32 v[78:79], v[106:107], v[78:79] op_sel_hi:[0,1]
	v_pk_mul_f32 v[76:77], v[106:107], v[76:77] op_sel_hi:[0,1]
	v_pk_fma_f32 v[96:97], v[88:89], v[192:193], v[96:97]
	v_pk_fma_f32 v[88:89], v[88:89], v[190:191], v[200:201]
	v_pk_mul_f32 v[58:59], v[106:107], v[58:59] op_sel_hi:[0,1]
	v_pk_mul_f32 v[56:57], v[106:107], v[56:57] op_sel_hi:[0,1]
	v_pk_mul_f32 v[4:5], v[106:107], v[6:7] op_sel_hi:[0,1]
	v_pk_mul_f32 v[2:3], v[106:107], v[10:11] op_sel_hi:[0,1]
	v_mov_b32_e32 v106, v107
	v_pk_mul_f32 v[10:11], v[132:133], s[100:101] op_sel_hi:[1,0]
	v_cvt_f32_i32_e32 v87, v87
	v_cvt_f32_i32_e32 v86, v86
	v_pk_mul_f32 v[198:199], v[198:199], v[202:203]
	v_pk_fma_f32 v[88:89], v[76:77], v[192:193], v[88:89]
	v_pk_mul_f32 v[200:201], v[76:77], v[196:197]
	v_pk_mul_f32 v[76:77], v[76:77], v[190:191]
	v_pk_mul_f32 v[178:179], v[214:215], v[178:179]
	v_cvt_f32_i32_e32 v7, v1
	v_cvt_f32_i32_e32 v6, v0
	v_pk_mul_f32 v[0:1], v[106:107], v[12:13]
	v_exp_f32_e32 v10, v10
	v_exp_f32_e32 v11, v11
	v_pk_mul_f32 v[12:13], v[136:137], s[100:101] op_sel_hi:[1,0]
	v_pk_mul_f32 v[102:103], v[112:113], v[102:103] op_sel:[1,0]
	v_pk_mul_f32 v[98:99], v[114:115], v[98:99] op_sel_hi:[0,1]
	v_pk_mul_f32 v[194:195], v[194:195], v[202:203]
	v_pk_fma_f32 v[92:93], v[84:85], v[192:193], v[92:93]
	v_pk_fma_f32 v[84:85], v[84:85], v[190:191], v[200:201]
	v_pk_fma_f32 v[76:77], v[242:243], v[196:197], v[76:77]
	v_pk_fma_f32 v[178:179], v[240:241], v[198:199], v[178:179]
	v_exp_f32_e32 v12, v12
	v_exp_f32_e32 v13, v13
	v_pk_mul_f32 v[94:95], v[208:209], v[94:95] op_sel_hi:[0,1]
	v_pk_fma_f32 v[84:85], v[242:243], v[192:193], v[84:85]
	v_pk_fma_f32 v[76:77], v[192:193], v[204:205], v[76:77]
	v_pk_fma_f32 v[190:191], v[102:103], v[194:195], v[178:179]
	v_pk_mul_f32 v[178:179], v[102:103], v[198:199]
	v_pk_mul_f32 v[192:193], v[98:99], v[198:199]
	v_pk_mul_f32 v[90:91], v[104:105], v[90:91] op_sel_hi:[0,1]
	v_pk_fma_f32 v[178:179], v[240:241], v[214:215], v[178:179]
	v_pk_fma_f32 v[102:103], v[102:103], v[214:215], v[192:193]
	v_pk_mul_f32 v[192:193], v[94:95], v[198:199]
	v_pk_mul_f32 v[86:87], v[104:105], v[86:87] op_sel:[1,0]
	v_pk_fma_f32 v[178:179], v[98:99], v[194:195], v[178:179]
	v_pk_fma_f32 v[98:99], v[98:99], v[214:215], v[192:193]
	v_pk_mul_f32 v[192:193], v[90:91], v[198:199]
	v_cvt_f32_i32_e32 v81, v81
	v_cvt_f32_i32_e32 v80, v80
	v_cvt_f32_i32_e32 v73, v73
	v_cvt_f32_i32_e32 v72, v72
	v_pk_add_f32 v[10:11], v[10:11], 1.0 op_sel_hi:[1,0]
	v_pk_fma_f32 v[102:103], v[94:95], v[194:195], v[102:103]
	v_pk_fma_f32 v[94:95], v[94:95], v[214:215], v[192:193]
	v_pk_mul_f32 v[192:193], v[86:87], v[198:199]
	v_cvt_f32_i32_e32 v69, v69
	v_cvt_f32_i32_e32 v68, v68
	v_rcp_f32_e32 v10, v10
	v_rcp_f32_e32 v11, v11
	v_pk_add_f32 v[12:13], v[12:13], 1.0 op_sel_hi:[1,0]
	v_pk_fma_f32 v[98:99], v[90:91], v[194:195], v[98:99]
	v_pk_fma_f32 v[90:91], v[90:91], v[214:215], v[192:193]
	v_pk_mul_f32 v[192:193], v[78:79], v[198:199]
	v_cvt_f32_i32_e32 v65, v65
	v_cvt_f32_i32_e32 v64, v64
	v_pk_mul_f32 v[160:161], v[160:161], v[168:169]
	v_rcp_f32_e32 v12, v12
	v_rcp_f32_e32 v13, v13
	v_pk_fma_f32 v[94:95], v[86:87], v[194:195], v[94:95]
	v_pk_fma_f32 v[86:87], v[86:87], v[214:215], v[192:193]
	v_cvt_f32_i32_e32 v61, v61
	v_cvt_f32_i32_e32 v60, v60
	v_pk_mul_f32 v[192:193], v[158:159], v[170:171]
	v_pk_mul_f32 v[158:159], v[156:157], v[168:169]
	v_pk_mul_f32 v[144:145], v[160:161], v[144:145]
	v_pk_mul_f32 v[80:81], v[112:113], v[80:81] op_sel:[1,0]
	v_pk_mul_f32 v[72:73], v[114:115], v[72:73] op_sel_hi:[0,1]
	v_pk_mul_f32 v[164:165], v[164:165], v[168:169]
	v_pk_fma_f32 v[144:145], v[236:237], v[158:159], v[144:145]
	v_pk_mul_f32 v[68:69], v[208:209], v[68:69] op_sel_hi:[0,1]
	v_pk_fma_f32 v[156:157], v[80:81], v[164:165], v[144:145]
	v_pk_mul_f32 v[144:145], v[80:81], v[158:159]
	v_pk_mul_f32 v[168:169], v[72:73], v[158:159]
	v_pk_mul_f32 v[10:11], v[132:133], v[10:11]
	v_cvt_f32_i32_e32 v83, v83
	v_cvt_f32_i32_e32 v82, v82
	v_pk_mul_f32 v[64:65], v[104:105], v[64:65] op_sel_hi:[0,1]
	v_pk_fma_f32 v[144:145], v[236:237], v[160:161], v[144:145]
	v_pk_fma_f32 v[80:81], v[80:81], v[160:161], v[168:169]
; __device__ __forceinline__ float silu_f(float x) { return x * __builtin_amdgcn_rcpf(1.0f + __expf(-x)); }
;     __device__ __forceinline__ void operator()(Acc& acc, const Unit& u, int wr, int wc, int fr, int fq, LAS unsigned char* lds, int tid) const {
;     ...
;         for (int ai = 0; ai < 2; ++ai)
; #pragma unroll
;             for (int m = 0; m < 4; ++m) {
;                 f32x4 a[2];
; #pragma unroll
;                 for (int n = 0; n < 2; ++n)
; #pragma unroll
;                     for (int e = 0; e < 4; ++e) a[n][e] = silu_f(acc[ai][0][m][n][e]) * acc[ai][1][m][n][e];
;                 store_h8_nt((h16*)((char*)ACT + (((tok0 + tl0 + 4u * ai + m) * (unsigned)FF + colo) << 1)), a[0], a[1]);
	v_pk_mul_f32 v[168:169], v[68:69], v[158:159]
	v_pk_mul_f32 v[106:107], v[10:11], v[188:189]
	v_pk_mul_f32 v[10:11], v[136:137], v[12:13]
	v_mul_f32_e32 v12, 0xbfb8aa3b, v156
	v_pk_mul_f32 v[60:61], v[104:105], v[60:61] op_sel:[1,0]
	v_pk_fma_f32 v[144:145], v[72:73], v[164:165], v[144:145]
	v_pk_fma_f32 v[72:73], v[72:73], v[160:161], v[168:169]
	v_pk_mul_f32 v[168:169], v[64:65], v[158:159]
	v_exp_f32_e32 v12, v12
	v_mul_f32_e32 v13, 0xbfb8aa3b, v157
	v_cvt_f32_i32_e32 v67, v67
	v_cvt_f32_i32_e32 v66, v66
	v_cvt_f32_i32_e32 v63, v63
	v_cvt_f32_i32_e32 v62, v62
	v_pk_mul_f32 v[162:163], v[162:163], v[170:171]
	v_pk_fma_f32 v[80:81], v[68:69], v[164:165], v[80:81]
	v_pk_fma_f32 v[68:69], v[68:69], v[160:161], v[168:169]
	v_pk_mul_f32 v[168:169], v[60:61], v[158:159]
	v_cvt_f32_i32_e32 v29, v29
	v_cvt_f32_i32_e32 v28, v28
	v_cvt_f32_i32_e32 v25, v25
	v_cvt_f32_i32_e32 v24, v24
	v_cvt_f32_i32_e32 v19, v19
	v_cvt_f32_i32_e32 v18, v18
	v_cvt_f32_i32_e32 v15, v15
	v_cvt_f32_i32_e32 v14, v14
	v_exp_f32_e32 v13, v13
	v_pk_fma_f32 v[72:73], v[64:65], v[164:165], v[72:73]
	v_pk_fma_f32 v[64:65], v[64:65], v[160:161], v[168:169]
	v_pk_mul_f32 v[146:147], v[162:163], v[146:147]
	v_pk_mul_f32 v[82:83], v[112:113], v[82:83] op_sel:[1,0]
	v_pk_mul_f32 v[166:167], v[166:167], v[170:171]
	v_pk_fma_f32 v[64:65], v[56:57], v[164:165], v[64:65]
	v_pk_mul_f32 v[168:169], v[56:57], v[158:159]
	v_pk_mul_f32 v[56:57], v[56:57], v[160:161]
	v_pk_fma_f32 v[146:147], v[232:233], v[192:193], v[146:147]
	v_cvt_f32_i32_e32 v75, v75
	v_cvt_f32_i32_e32 v74, v74
	v_pk_fma_f32 v[56:57], v[234:235], v[158:159], v[56:57]
	v_pk_fma_f32 v[158:159], v[82:83], v[166:167], v[146:147]
	v_cvt_f32_i32_e32 v23, v23
	v_cvt_f32_i32_e32 v22, v22
	v_cvt_f32_i32_e32 v21, v21
	v_cvt_f32_i32_e32 v20, v20
	v_pk_mul_f32 v[132:133], v[10:11], v[190:191]
	v_add_f32_e32 v10, 1.0, v12
	v_pk_mul_f32 v[66:67], v[104:105], v[66:67] op_sel_hi:[0,1]
	v_pk_mul_f32 v[62:63], v[104:105], v[62:63] op_sel:[1,0]
	v_pk_fma_f32 v[38:39], v[218:219], v[134:135], v[38:39]
	v_pk_mul_f32 v[134:135], v[228:229], v[28:29]
	v_pk_mul_f32 v[112:113], v[112:113], v[24:25] op_sel:[1,0]
	v_pk_mul_f32 v[28:29], v[208:209], v[18:19] op_sel_hi:[0,1]
	v_pk_mul_f32 v[24:25], v[104:105], v[14:15] op_sel_hi:[0,1]
	v_rcp_f32_e32 v104, v10
	v_add_f32_e32 v10, 1.0, v13
	s_waitcnt vmcnt(0)
	v_pk_mul_f32 v[18:19], v[116:117], v[180:181]
	v_mul_f32_e32 v116, 0xbfb8aa3b, v158
	v_pk_mul_f32 v[6:7], v[226:227], v[6:7]
	v_rcp_f32_e32 v105, v10
	v_pk_mul_f32 v[10:11], v[118:119], v[182:183]
	v_exp_f32_e32 v118, v116
	v_mul_f32_e32 v116, 0xbfb8aa3b, v159
	v_mov_b32_dpp v148, v6 row_shr:1 row_mask:0xf bank_mask:0xf
	v_mov_b32_dpp v149, v7 row_shr:1 row_mask:0xf bank_mask:0xf
	v_exp_f32_e32 v119, v116
	v_pk_mul_f32 v[74:75], v[114:115], v[74:75] op_sel_hi:[0,1]
	v_pk_mul_f32 v[52:53], v[114:115], v[22:23] op_sel_hi:[0,1]
	v_pk_mul_f32 v[54:55], v[114:115], v[20:21] op_sel_hi:[0,1]
	v_pk_mul_f32 v[20:21], v[184:185], v[180:181]
	v_pk_mul_f32 v[114:115], v[18:19], v[148:149]
	v_pk_mul_f32 v[22:23], v[152:153], v[180:181]
	v_pk_fma_f32 v[114:115], v[134:135], v[20:21], v[114:115]
	v_pk_mul_f32 v[104:105], v[156:157], v[104:105]
	v_pk_fma_f32 v[114:115], v[112:113], v[22:23], v[114:115]
	v_mov_b32_dpp v150, v0 row_shr:1 row_mask:0xf bank_mask:0xf
	v_pk_mul_f32 v[116:117], v[104:105], v[114:115]
	v_pk_add_f32 v[104:105], v[118:119], 1.0 op_sel_hi:[1,0]
	v_rcp_f32_e32 v104, v104
	v_rcp_f32_e32 v105, v105
	v_mov_b32_dpp v151, v1 row_shr:1 row_mask:0xf bank_mask:0xf
	v_pk_mul_f32 v[12:13], v[186:187], v[182:183]
	v_pk_mul_f32 v[114:115], v[10:11], v[150:151]
	v_pk_mul_f32 v[14:15], v[154:155], v[182:183]
	v_pk_fma_f32 v[114:115], v[126:127], v[12:13], v[114:115]
	v_pk_mul_f32 v[104:105], v[158:159], v[104:105]
	v_pk_fma_f32 v[114:115], v[124:125], v[14:15], v[114:115]
	s_movk_i32 s0, 0x1600
	v_pk_mul_f32 v[118:119], v[104:105], v[114:115]
	v_mul_f32_e32 v105, 0xbfb8aa3b, v128
	v_cvt_pk_f16_f32 v114, v106, v107
	v_exp_f32_e32 v105, v105
	v_mul_f32_e32 v106, 0xbfb8aa3b, v129
	v_exp_f32_e32 v107, v106
	v_mul_lo_u32 v104, v212, s0
	v_add_f32_e32 v105, 1.0, v105
	v_add_lshl_u32 v104, v104, v213, 1
	v_cvt_pk_f16_f32 v115, v132, v133
	v_cvt_pk_f16_f32 v116, v116, v117
	v_cvt_pk_f16_f32 v117, v118, v119
	v_rcp_f32_e32 v106, v105
	v_add_f32_e32 v105, 1.0, v107
	v_mul_f32_e32 v107, 0xbfb8aa3b, v130
	global_store_dwordx4 v104, v[114:117], s[14:15] nt
	v_pk_mul_f32 v[146:147], v[82:83], v[192:193]
	v_mov_b32_dpp v110, v126 row_shl:1 row_mask:0xf bank_mask:0xf
	v_exp_f32_e32 v114, v107
	v_mul_f32_e32 v107, 0xbfb8aa3b, v131
	v_exp_f32_e32 v115, v107
	v_rcp_f32_e32 v107, v105
	v_add_f32_e32 v105, 1.0, v114
	v_rcp_f32_e32 v114, v105
	v_add_f32_e32 v105, 1.0, v115
	v_rcp_f32_e32 v115, v105
	v_mul_f32_e32 v105, 0xbfb8aa3b, v144
	v_exp_f32_e32 v105, v105
	v_mul_f32_e32 v116, 0xbfb8aa3b, v145
	v_exp_f32_e32 v118, v116
	v_pk_fma_f32 v[146:147], v[232:233], v[162:163], v[146:147]
	v_pk_mul_f32 v[114:115], v[130:131], v[114:115]
	v_add_f32_e32 v105, 1.0, v105
	v_pk_fma_f32 v[146:147], v[74:75], v[166:167], v[146:147]
	v_pk_mul_f32 v[116:117], v[114:115], v[178:179]
	v_rcp_f32_e32 v114, v105
	v_add_f32_e32 v105, 1.0, v118
	v_rcp_f32_e32 v115, v105
	v_mul_f32_e32 v105, 0xbfb8aa3b, v146
	v_pk_mul_f32 v[106:107], v[128:129], v[106:107]
	v_exp_f32_e32 v105, v105
	v_mul_f32_e32 v128, 0xbfb8aa3b, v147
	v_exp_f32_e32 v128, v128
	v_pk_mul_f32 v[118:119], v[112:113], v[20:21]
	v_pk_mul_f32 v[114:115], v[144:145], v[114:115]
	v_pk_fma_f32 v[118:119], v[134:135], v[18:19], v[118:119]
	v_add_f32_e32 v105, 1.0, v105
	v_pk_fma_f32 v[118:119], v[54:55], v[22:23], v[118:119]
; __device__ __forceinline__ float silu_f(float x) { return x * __builtin_amdgcn_rcpf(1.0f + __expf(-x)); }
;     __device__ __forceinline__ void operator()(Acc& acc, const Unit& u, int wr, int wc, int fr, int fq, LAS unsigned char* lds, int tid) const {
;     ...
;         for (int ai = 0; ai < 2; ++ai)
; #pragma unroll
;             for (int m = 0; m < 4; ++m) {
;                 f32x4 a[2];
; #pragma unroll
;                 for (int n = 0; n < 2; ++n)
; #pragma unroll
;                     for (int e = 0; e < 4; ++e) a[n][e] = silu_f(acc[ai][0][m][n][e]) * acc[ai][1][m][n][e];
;                 store_h8_nt((h16*)((char*)ACT + (((tok0 + tl0 + 4u * ai + m) * (unsigned)FF + colo) << 1)), a[0], a[1]);
	v_mov_b32_dpp v111, v127 row_shl:1 row_mask:0xf bank_mask:0xf
	v_pk_mul_f32 v[118:119], v[114:115], v[118:119]
	v_rcp_f32_e32 v114, v105
	v_add_f32_e32 v105, 1.0, v128
	v_rcp_f32_e32 v115, v105
	v_pk_mul_f32 v[128:129], v[124:125], v[12:13]
	v_pk_mul_f32 v[106:107], v[106:107], v[176:177]
	v_pk_fma_f32 v[126:127], v[126:127], v[10:11], v[128:129]
	v_pk_mul_f32 v[114:115], v[146:147], v[114:115]
	v_pk_fma_f32 v[126:127], v[52:53], v[14:15], v[126:127]
	v_add_u32_e32 v105, 0x2c00, v104
	v_pk_mul_f32 v[126:127], v[114:115], v[126:127]
	v_cvt_pk_f16_f32 v114, v106, v107
	v_mul_f32_e32 v106, 0xbfb8aa3b, v120
	v_exp_f32_e32 v106, v106
	v_mul_f32_e32 v107, 0xbfb8aa3b, v121
	v_exp_f32_e32 v107, v107
	v_cvt_pk_f16_f32 v115, v116, v117
	v_cvt_pk_f16_f32 v116, v118, v119
	v_cvt_pk_f16_f32 v117, v126, v127
	global_store_dwordx4 v105, v[114:117], s[14:15] nt
	v_add_f32_e32 v105, 1.0, v106
	v_rcp_f32_e32 v106, v105
	v_add_f32_e32 v105, 1.0, v107
	v_mul_f32_e32 v107, 0xbfb8aa3b, v122
	v_exp_f32_e32 v114, v107
	v_mul_f32_e32 v107, 0xbfb8aa3b, v123
	v_exp_f32_e32 v115, v107
	v_rcp_f32_e32 v107, v105
	v_add_f32_e32 v105, 1.0, v114
	v_rcp_f32_e32 v114, v105
	v_add_f32_e32 v105, 1.0, v115
	v_rcp_f32_e32 v115, v105
	v_pk_mul_f32 v[106:107], v[120:121], v[106:107]
	v_mul_f32_e32 v105, 0xbfb8aa3b, v80
	v_pk_mul_f32 v[100:101], v[106:107], v[100:101]
	v_pk_mul_f32 v[106:107], v[122:123], v[114:115]
	v_exp_f32_e32 v105, v105
	v_mul_f32_e32 v114, 0xbfb8aa3b, v81
	v_exp_f32_e32 v114, v114
	v_cvt_f32_i32_e32 v71, v71
	v_cvt_f32_i32_e32 v70, v70
	v_add_f32_e32 v105, 1.0, v105
	v_pk_mul_f32 v[102:103], v[106:107], v[102:103]
	v_rcp_f32_e32 v106, v105
	v_add_f32_e32 v105, 1.0, v114
	v_rcp_f32_e32 v107, v105
	v_pk_fma_f32 v[68:69], v[60:61], v[164:165], v[68:69]
	v_pk_fma_f32 v[60:61], v[60:61], v[160:161], v[168:169]
	v_pk_mul_f32 v[160:161], v[74:75], v[192:193]
	v_pk_mul_f32 v[70:71], v[208:209], v[70:71] op_sel_hi:[0,1]
	v_pk_fma_f32 v[82:83], v[82:83], v[162:163], v[160:161]
	v_pk_mul_f32 v[114:115], v[54:55], v[20:21]
	v_pk_fma_f32 v[82:83], v[70:71], v[166:167], v[82:83]
	v_pk_mul_f32 v[80:81], v[80:81], v[106:107]
	v_mul_f32_e32 v105, 0xbfb8aa3b, v82
	v_mul_f32_e32 v106, 0xbfb8aa3b, v83
	v_pk_fma_f32 v[112:113], v[112:113], v[18:19], v[114:115]
	v_exp_f32_e32 v105, v105
	v_exp_f32_e32 v114, v106
	v_pk_fma_f32 v[112:113], v[30:31], v[22:23], v[112:113]
	v_pk_mul_f32 v[160:161], v[70:71], v[192:193]
	v_pk_mul_f32 v[106:107], v[80:81], v[112:113]
	v_add_f32_e32 v80, 1.0, v105
	v_add_f32_e32 v81, 1.0, v114
	v_rcp_f32_e32 v80, v80
	v_rcp_f32_e32 v81, v81
	v_pk_mul_f32 v[112:113], v[52:53], v[12:13]
	v_add_u32_e32 v105, 0x5800, v104
	v_pk_fma_f32 v[112:113], v[124:125], v[10:11], v[112:113]
	v_pk_mul_f32 v[80:81], v[82:83], v[80:81]
	v_pk_fma_f32 v[112:113], v[28:29], v[14:15], v[112:113]
	v_cvt_pk_f16_f32 v82, v106, v107
	v_pk_mul_f32 v[112:113], v[80:81], v[112:113]
	v_cvt_pk_f16_f32 v80, v100, v101
	v_pk_mul_f32 v[100:101], v[48:49], s[100:101] op_sel_hi:[1,0]
	v_exp_f32_e32 v100, v100
	v_exp_f32_e32 v101, v101
	v_cvt_pk_f16_f32 v81, v102, v103
	v_cvt_pk_f16_f32 v83, v112, v113
	global_store_dwordx4 v105, v[80:83], s[14:15] nt
	v_pk_fma_f32 v[74:75], v[74:75], v[162:163], v[160:161]
	v_pk_mul_f32 v[160:161], v[66:67], v[192:193]
	v_pk_add_f32 v[80:81], v[100:101], 1.0 op_sel_hi:[1,0]
	v_rcp_f32_e32 v80, v80
	v_rcp_f32_e32 v81, v81
	v_pk_mul_f32 v[82:83], v[50:51], s[100:101] op_sel_hi:[1,0]
	v_exp_f32_e32 v82, v82
	v_pk_mul_f32 v[48:49], v[48:49], v[80:81]
	v_pk_mul_f32 v[80:81], v[72:73], s[100:101] op_sel_hi:[1,0]
	v_exp_f32_e32 v80, v80
	v_exp_f32_e32 v81, v81
	v_exp_f32_e32 v83, v83
	v_pk_add_f32 v[80:81], v[80:81], 1.0 op_sel_hi:[1,0]
	v_rcp_f32_e32 v80, v80
	v_rcp_f32_e32 v81, v81
	v_pk_add_f32 v[82:83], v[82:83], 1.0 op_sel_hi:[1,0]
	v_rcp_f32_e32 v82, v82
	v_rcp_f32_e32 v83, v83
	v_pk_fma_f32 v[74:75], v[66:67], v[166:167], v[74:75]
	v_pk_mul_f32 v[72:73], v[72:73], v[80:81]
	v_pk_mul_f32 v[80:81], v[74:75], s[100:101] op_sel_hi:[1,0]
	v_exp_f32_e32 v80, v80
	v_exp_f32_e32 v81, v81
	v_pk_mul_f32 v[50:51], v[50:51], v[82:83]
	v_pk_mul_f32 v[82:83], v[30:31], v[20:21]
	v_pk_mul_f32 v[48:49], v[48:49], v[96:97]
	v_pk_fma_f32 v[54:55], v[54:55], v[18:19], v[82:83]
	v_pk_mul_f32 v[50:51], v[50:51], v[98:99]
	v_pk_fma_f32 v[54:55], v[26:27], v[22:23], v[54:55]
	v_cvt_pk_f16_f32 v48, v48, v49
	v_pk_mul_f32 v[54:55], v[72:73], v[54:55]
	v_pk_add_f32 v[72:73], v[80:81], 1.0 op_sel_hi:[1,0]
	v_rcp_f32_e32 v72, v72
	v_rcp_f32_e32 v73, v73
	v_pk_mul_f32 v[80:81], v[28:29], v[12:13]
	v_cvt_pk_f16_f32 v49, v50, v51
	v_pk_fma_f32 v[52:53], v[52:53], v[10:11], v[80:81]
	v_pk_mul_f32 v[72:73], v[74:75], v[72:73]
	v_pk_fma_f32 v[52:53], v[24:25], v[14:15], v[52:53]
	v_cvt_pk_f16_f32 v50, v54, v55
	v_pk_mul_f32 v[52:53], v[72:73], v[52:53]
	v_add_u32_e32 v72, 0x8400, v104
	v_cvt_pk_f16_f32 v51, v52, v53
	v_pk_mul_f32 v[52:53], v[44:45], s[100:101] op_sel_hi:[1,0]
	v_exp_f32_e32 v52, v52
	v_exp_f32_e32 v53, v53
	global_store_dwordx4 v72, v[48:51], s[14:15] nt
	v_pk_fma_f32 v[70:71], v[70:71], v[162:163], v[160:161]
	v_pk_mul_f32 v[160:161], v[62:63], v[192:193]
	v_pk_add_f32 v[48:49], v[52:53], 1.0 op_sel_hi:[1,0]
	v_pk_mul_f32 v[50:51], v[46:47], s[100:101] op_sel_hi:[1,0]
	v_rcp_f32_e32 v48, v48
	v_exp_f32_e32 v50, v50
	v_exp_f32_e32 v51, v51
	v_rcp_f32_e32 v49, v49
	v_pk_fma_f32 v[70:71], v[62:63], v[166:167], v[70:71]
	v_pk_add_f32 v[50:51], v[50:51], 1.0 op_sel_hi:[1,0]
	v_pk_mul_f32 v[44:45], v[44:45], v[48:49]
	v_pk_mul_f32 v[48:49], v[68:69], s[100:101] op_sel_hi:[1,0]
	v_rcp_f32_e32 v50, v50
	v_rcp_f32_e32 v51, v51
	v_exp_f32_e32 v48, v48
	v_exp_f32_e32 v49, v49
; __device__ __forceinline__ float silu_f(float x) { return x * __builtin_amdgcn_rcpf(1.0f + __expf(-x)); }
;     __device__ __forceinline__ void operator()(Acc& acc, const Unit& u, int wr, int wc, int fr, int fq, LAS unsigned char* lds, int tid) const {
;     ...
;         for (int ai = 0; ai < 2; ++ai)
; #pragma unroll
;             for (int m = 0; m < 4; ++m) {
;                 f32x4 a[2];
; #pragma unroll
;                 for (int n = 0; n < 2; ++n)
; #pragma unroll
;                     for (int e = 0; e < 4; ++e) a[n][e] = silu_f(acc[ai][0][m][n][e]) * acc[ai][1][m][n][e];
;                 store_h8_nt((h16*)((char*)ACT + (((tok0 + tl0 + 4u * ai + m) * (unsigned)FF + colo) << 1)), a[0], a[1]);
	v_pk_mul_f32 v[44:45], v[44:45], v[92:93]
	v_pk_mul_f32 v[46:47], v[46:47], v[50:51]
	v_pk_add_f32 v[48:49], v[48:49], 1.0 op_sel_hi:[1,0]
	v_pk_mul_f32 v[50:51], v[26:27], v[20:21]
	v_rcp_f32_e32 v48, v48
	v_rcp_f32_e32 v49, v49
	v_pk_fma_f32 v[30:31], v[30:31], v[18:19], v[50:51]
	v_pk_mul_f32 v[50:51], v[70:71], s[100:101] op_sel_hi:[1,0]
	v_exp_f32_e32 v50, v50
	v_exp_f32_e32 v51, v51
	v_pk_fma_f32 v[30:31], v[16:17], v[22:23], v[30:31]
	v_pk_mul_f32 v[48:49], v[68:69], v[48:49]
	v_pk_mul_f32 v[46:47], v[46:47], v[94:95]
	v_pk_mul_f32 v[30:31], v[48:49], v[30:31]
	v_pk_add_f32 v[48:49], v[50:51], 1.0 op_sel_hi:[1,0]
	v_rcp_f32_e32 v48, v48
	v_rcp_f32_e32 v49, v49
	v_pk_mul_f32 v[50:51], v[24:25], v[12:13]
	v_cvt_pk_f16_f32 v30, v30, v31
	v_pk_fma_f32 v[28:29], v[28:29], v[10:11], v[50:51]
	v_pk_mul_f32 v[48:49], v[70:71], v[48:49]
	v_pk_fma_f32 v[28:29], v[8:9], v[14:15], v[28:29]
	v_add_u32_e32 v50, 0xb000, v104
	v_pk_mul_f32 v[48:49], v[48:49], v[28:29]
	v_cvt_pk_f16_f32 v28, v44, v45
	v_pk_mul_f32 v[44:45], v[40:41], s[100:101] op_sel_hi:[1,0]
	v_exp_f32_e32 v44, v44
	v_exp_f32_e32 v45, v45
	v_cvt_pk_f16_f32 v29, v46, v47
	v_cvt_pk_f16_f32 v31, v48, v49
	global_store_dwordx4 v50, v[28:31], s[14:15] nt
	v_pk_fma_f32 v[66:67], v[66:67], v[162:163], v[160:161]
	v_pk_fma_f32 v[90:91], v[78:79], v[194:195], v[90:91]
	v_pk_add_f32 v[28:29], v[44:45], 1.0 op_sel_hi:[1,0]
	v_pk_mul_f32 v[30:31], v[42:43], s[100:101] op_sel_hi:[1,0]
	v_rcp_f32_e32 v28, v28
	v_exp_f32_e32 v30, v30
	v_exp_f32_e32 v31, v31
	v_rcp_f32_e32 v29, v29
	v_pk_fma_f32 v[66:67], v[58:59], v[166:167], v[66:67]
	v_pk_add_f32 v[30:31], v[30:31], 1.0 op_sel_hi:[1,0]
	v_pk_mul_f32 v[28:29], v[40:41], v[28:29]
	v_pk_mul_f32 v[40:41], v[64:65], s[100:101] op_sel_hi:[1,0]
	v_rcp_f32_e32 v30, v30
	v_rcp_f32_e32 v31, v31
	v_exp_f32_e32 v40, v40
	v_exp_f32_e32 v41, v41
	v_pk_mul_f32 v[28:29], v[28:29], v[88:89]
	v_pk_mul_f32 v[30:31], v[42:43], v[30:31]
	v_pk_add_f32 v[40:41], v[40:41], 1.0 op_sel_hi:[1,0]
	v_pk_mul_f32 v[42:43], v[16:17], v[20:21]
	v_rcp_f32_e32 v40, v40
	v_rcp_f32_e32 v41, v41
	v_pk_fma_f32 v[26:27], v[26:27], v[18:19], v[42:43]
	v_pk_mul_f32 v[42:43], v[66:67], s[100:101] op_sel_hi:[1,0]
	v_exp_f32_e32 v42, v42
	v_exp_f32_e32 v43, v43
	v_pk_fma_f32 v[26:27], v[2:3], v[22:23], v[26:27]
	v_pk_mul_f32 v[40:41], v[64:65], v[40:41]
	v_pk_mul_f32 v[30:31], v[30:31], v[90:91]
	v_pk_mul_f32 v[26:27], v[40:41], v[26:27]
	v_pk_add_f32 v[40:41], v[42:43], 1.0 op_sel_hi:[1,0]
	v_rcp_f32_e32 v40, v40
	v_rcp_f32_e32 v41, v41
	v_pk_mul_f32 v[42:43], v[8:9], v[12:13]
	v_pk_fma_f32 v[60:61], v[234:235], v[164:165], v[60:61]
	v_pk_fma_f32 v[24:25], v[24:25], v[10:11], v[42:43]
	v_pk_mul_f32 v[40:41], v[66:67], v[40:41]
	v_pk_fma_f32 v[24:25], v[4:5], v[14:15], v[24:25]
	v_add_u32_e32 v42, 0xdc00, v104
	v_pk_mul_f32 v[40:41], v[40:41], v[24:25]
	v_cvt_pk_f16_f32 v24, v28, v29
	v_pk_mul_f32 v[28:29], v[36:37], s[100:101] op_sel_hi:[1,0]
	v_exp_f32_e32 v28, v28
	v_exp_f32_e32 v29, v29
	v_cvt_pk_f16_f32 v25, v30, v31
	v_cvt_pk_f16_f32 v26, v26, v27
	v_cvt_pk_f16_f32 v27, v40, v41
	global_store_dwordx4 v42, v[24:27], s[14:15] nt
	v_pk_mul_f32 v[160:161], v[58:59], v[192:193]
	v_pk_mul_f32 v[30:31], v[2:3], v[20:21]
	v_pk_add_f32 v[24:25], v[28:29], 1.0 op_sel_hi:[1,0]
	v_pk_mul_f32 v[28:29], v[60:61], s[100:101] op_sel_hi:[1,0]
	v_exp_f32_e32 v28, v28
	v_exp_f32_e32 v29, v29
	v_pk_fma_f32 v[62:63], v[62:63], v[162:163], v[160:161]
	v_pk_fma_f32 v[62:63], v[230:231], v[166:167], v[62:63]
	v_pk_add_f32 v[28:29], v[28:29], 1.0 op_sel_hi:[1,0]
	v_pk_mul_f32 v[26:27], v[38:39], s[100:101] op_sel_hi:[1,0]
; __device__ __forceinline__ float silu_f(float x) { return x * __builtin_amdgcn_rcpf(1.0f + __expf(-x)); }
;     __device__ __forceinline__ void operator()(Acc& acc, const Unit& u, int wr, int wc, int fr, int fq, LAS unsigned char* lds, int tid) const {
;     ...
;         for (int ai = 0; ai < 2; ++ai)
; #pragma unroll
;             for (int m = 0; m < 4; ++m) {
;                 f32x4 a[2];
; #pragma unroll
;                 for (int n = 0; n < 2; ++n)
; #pragma unroll
;                     for (int e = 0; e < 4; ++e) a[n][e] = silu_f(acc[ai][0][m][n][e]) * acc[ai][1][m][n][e];
;                 store_h8_nt((h16*)((char*)ACT + (((tok0 + tl0 + 4u * ai + m) * (unsigned)FF + colo) << 1)), a[0], a[1]);
;                 asm volatile("" ::: "memory");
;             }
;     }
	v_rcp_f32_e32 v28, v28
	v_rcp_f32_e32 v29, v29
	v_pk_fma_f32 v[16:17], v[16:17], v[18:19], v[30:31]
	v_pk_mul_f32 v[30:31], v[62:63], s[100:101] op_sel_hi:[1,0]
	v_exp_f32_e32 v26, v26
	v_exp_f32_e32 v27, v27
	v_exp_f32_e32 v30, v30
	v_exp_f32_e32 v31, v31
	v_pk_fma_f32 v[16:17], v[6:7], v[22:23], v[16:17]
	v_pk_mul_f32 v[28:29], v[60:61], v[28:29]
	v_pk_add_f32 v[26:27], v[26:27], 1.0 op_sel_hi:[1,0]
	v_pk_mul_f32 v[16:17], v[28:29], v[16:17]
	v_pk_add_f32 v[28:29], v[30:31], 1.0 op_sel_hi:[1,0]
	v_rcp_f32_e32 v24, v24
	v_rcp_f32_e32 v25, v25
	v_rcp_f32_e32 v26, v26
	v_rcp_f32_e32 v27, v27
	v_rcp_f32_e32 v28, v28
	v_rcp_f32_e32 v29, v29
	v_pk_mul_f32 v[30:31], v[4:5], v[12:13]
	v_pk_fma_f32 v[86:87], v[238:239], v[194:195], v[86:87]
	v_pk_fma_f32 v[8:9], v[8:9], v[10:11], v[30:31]
	v_pk_mul_f32 v[24:25], v[36:37], v[24:25]
	v_pk_mul_f32 v[26:27], v[38:39], v[26:27]
	v_pk_fma_f32 v[8:9], v[0:1], v[14:15], v[8:9]
	v_pk_mul_f32 v[28:29], v[62:63], v[28:29]
	v_pk_mul_f32 v[24:25], v[24:25], v[84:85]
	v_pk_mul_f32 v[26:27], v[26:27], v[86:87]
	v_pk_mul_f32 v[8:9], v[28:29], v[8:9]
	v_pk_fma_f32 v[56:57], v[164:165], v[172:173], v[56:57]
	v_add_u32_e32 v28, 0x10800, v104
	v_cvt_pk_f16_f32 v24, v24, v25
	v_cvt_pk_f16_f32 v25, v26, v27
	v_cvt_pk_f16_f32 v26, v16, v17
	v_cvt_pk_f16_f32 v27, v8, v9
	global_store_dwordx4 v28, v[24:27], s[14:15] nt
	v_pk_mul_f32 v[58:59], v[58:59], v[162:163]
	s_nop 0
	v_pk_mul_f32 v[24:25], v[56:57], s[100:101] op_sel_hi:[1,0]
	v_exp_f32_e32 v24, v24
	v_exp_f32_e32 v25, v25
	v_pk_fma_f32 v[58:59], v[230:231], v[192:193], v[58:59]
	v_pk_mul_f32 v[8:9], v[32:33], s[100:101] op_sel_hi:[1,0]
	v_pk_fma_f32 v[58:59], v[166:167], v[174:175], v[58:59]
	v_pk_add_f32 v[24:25], v[24:25], 1.0 op_sel_hi:[1,0]
	v_pk_mul_f32 v[16:17], v[34:35], s[100:101] op_sel_hi:[1,0]
	v_rcp_f32_e32 v24, v24
	v_rcp_f32_e32 v25, v25
	v_pk_mul_f32 v[2:3], v[2:3], v[18:19]
	v_pk_mul_f32 v[18:19], v[58:59], s[100:101] op_sel_hi:[1,0]
	v_exp_f32_e32 v8, v8
	v_exp_f32_e32 v9, v9
	v_exp_f32_e32 v16, v16
	v_exp_f32_e32 v17, v17
	v_exp_f32_e32 v18, v18
	v_exp_f32_e32 v19, v19
	v_mov_b32_dpp v108, v134 row_shl:1 row_mask:0xf bank_mask:0xf
	v_mov_b32_dpp v109, v135 row_shl:1 row_mask:0xf bank_mask:0xf
	v_pk_fma_f32 v[2:3], v[6:7], v[20:21], v[2:3]
	v_pk_mul_f32 v[6:7], v[56:57], v[24:25]
	v_pk_fma_f32 v[2:3], v[22:23], v[108:109], v[2:3]
	v_pk_add_f32 v[8:9], v[8:9], 1.0 op_sel_hi:[1,0]
	v_pk_add_f32 v[16:17], v[16:17], 1.0 op_sel_hi:[1,0]
	v_pk_mul_f32 v[2:3], v[6:7], v[2:3]
	v_pk_add_f32 v[6:7], v[18:19], 1.0 op_sel_hi:[1,0]
	v_rcp_f32_e32 v8, v8
	v_rcp_f32_e32 v9, v9
	v_rcp_f32_e32 v16, v16
	v_rcp_f32_e32 v17, v17
	v_rcp_f32_e32 v6, v6
	v_rcp_f32_e32 v7, v7
	v_pk_mul_f32 v[78:79], v[78:79], v[214:215]
	v_pk_mul_f32 v[4:5], v[4:5], v[10:11]
	v_pk_fma_f32 v[78:79], v[238:239], v[198:199], v[78:79]
	v_pk_fma_f32 v[0:1], v[0:1], v[12:13], v[4:5]
	v_pk_fma_f32 v[78:79], v[194:195], v[206:207], v[78:79]
	v_pk_mul_f32 v[8:9], v[32:33], v[8:9]
	v_pk_mul_f32 v[16:17], v[34:35], v[16:17]
	v_pk_fma_f32 v[0:1], v[14:15], v[110:111], v[0:1]
	v_pk_mul_f32 v[4:5], v[58:59], v[6:7]
	v_pk_mul_f32 v[8:9], v[8:9], v[76:77]
	v_pk_mul_f32 v[16:17], v[16:17], v[78:79]
	v_pk_mul_f32 v[4:5], v[4:5], v[0:1]
	v_add_u32_e32 v6, 0x13400, v104
	v_cvt_pk_f16_f32 v0, v8, v9
	v_cvt_pk_f16_f32 v1, v16, v17
	v_cvt_pk_f16_f32 v2, v2, v3
	v_cvt_pk_f16_f32 v3, v4, v5
	global_store_dwordx4 v6, v[0:3], s[14:15] nt
	s_andn2_b64 vcc, exec, s[36:37]
	s_mov_b64 s[36:37], -1
	s_cbranch_vccnz .LBB0_1061
	s_andn2_b64 vcc, exec, s[16:17]
	s_cbranch_vccnz .LBB0_1060
	s_barrier
	s_branch .LBB0_1060
